# PEER w phase: the 8 partial loads plus gate and expert-id loads of an iteration issued together (saddr form) instead of dependent load-wait-add steps
# speedup vs baseline: 1.0180x; 1.0011x over previous
; __device__ __forceinline__ int get_tid() { int t = threadIdx.x; asm volatile("" : "+v"(t)); return t; }
; __device__ __forceinline__ int get_bid() { int b = blockIdx.x; asm volatile("" : "+s"(b)); return b; }
; __device__ __forceinline__ void peer_w_phase(const Params& p, int l) {
;     const int tid = get_tid();
;     for (size_t i = ((size_t)get_bid() * NTHREADS + tid) * 4; i < (size_t)T * 128; i += (size_t)gridDim.x * NTHREADS * 4) {
;         f32x4 hs = __builtin_nontemporal_load((const f32x4*)(p.part + i));
; #pragma unroll
;         for (int xx = 1; xx < 8; ++xx) hs += __builtin_nontemporal_load((const f32x4*)(p.part + (size_t)xx * T * 128 + i));
;         const int4 e = *(const int4*)(p.experts + i);
;         const f32x4 gt = *(const f32x4*)(p.gates + i);
;         const float* su = p.su + l * 16384; const float* sv = p.sv + l * 16384;
.LBB0_22:
	v_readlane_b32 s0, v167, 35
	s_add_i32 s0, s0, -1
	s_mul_hi_i32 s1, s0, 0x38e38e39
	s_lshr_b32 s9, s1, 31
	s_ashr_i32 s1, s1, 1
	s_add_i32 s10, s1, s9
	s_mov_b32 s8, s10
	s_mul_i32 s1, s10, 9
	v_writelane_b32 v167, s8, 36
	s_sub_i32 s64, s0, s1
	s_mov_b64 s[0:1], -1
	v_writelane_b32 v167, s9, 37
	s_mov_b64 s[16:17], 0
	s_cmp_lt_i32 s64, 3
	s_mov_b64 s[8:9], 0
	s_cbranch_scc1 .LBB0_81
	s_cmp_gt_i32 s64, 4
	s_cbranch_scc0 .LBB0_38
	s_cmp_gt_i32 s64, 6
	s_cbranch_scc0 .LBB0_31
	s_cmp_eq_u32 s64, 7
	s_mov_b64 s[8:9], -1
	s_cbranch_scc0 .LBB0_30
	v_mov_b32_e32 v0, v126
	s_mov_b32 s36, s2
	s_ashr_i32 s37, s36, 31
	s_waitcnt lgkmcnt(0)
	v_ashrrev_i32_e32 v1, 31, v0
	s_lshl_b64 s[0:1], s[36:37], 10
	v_lshl_add_u64 v[4:5], v[0:1], 2, s[0:1]
	s_mov_b64 s[0:1], 0x400000
	s_mov_b32 s13, s65
	v_cmp_gt_u64_e32 vcc, s[0:1], v[4:5]
	s_and_saveexec_b64 s[0:1], vcc
	v_readlane_b32 s8, v166, 10
	v_readlane_b32 s14, v167, 11
	v_readlane_b32 s9, v166, 11
	v_readlane_b32 s15, v167, 12
	s_cbranch_execz .LBB0_29
	v_readlane_b32 s10, v167, 36
	v_readlane_b32 s11, v167, 37
	s_lshl_b32 s10, s10, 14
	s_ashr_i32 s11, s10, 31
	v_readlane_b32 s40, v165, 26
	s_lshl_b64 s[10:11], s[10:11], 2
	v_readlane_b32 s48, v165, 34
	v_readlane_b32 s49, v165, 35
	s_add_u32 s22, s48, s10
	v_readlane_b32 s50, v165, 36
	s_addc_u32 s23, s49, s11
	v_readlane_b32 s41, v165, 27
	v_readlane_b32 s42, v165, 28
	v_readlane_b32 s43, v165, 29
	v_readlane_b32 s44, v165, 30
	v_readlane_b32 s45, v165, 31
	v_readlane_b32 s46, v165, 32
	v_readlane_b32 s47, v165, 33
	v_readlane_b32 s51, v165, 37
	s_add_u32 s34, s50, s10
	s_addc_u32 s35, s51, s11
	s_lshl_b64 s[10:11], s[36:37], 12
	v_readlane_b32 s36, v165, 42
	v_readlane_b32 s42, v165, 48
	v_readlane_b32 s37, v165, 43
	v_readlane_b32 s43, v165, 49
	s_add_u32 s36, s42, s10
	v_readlane_b32 s40, v165, 46
	s_addc_u32 s37, s43, s11
	v_readlane_b32 s12, v167, 13
	v_readlane_b32 s41, v165, 47
	s_add_u32 s40, s12, s10
	v_readlane_b32 s12, v167, 14
	v_readlane_b32 s38, v165, 44
	s_addc_u32 s41, s12, s11
	v_readlane_b32 s39, v165, 45
	s_add_u32 s42, s38, s10
	v_readlane_b32 s44, v165, 50
	s_addc_u32 s43, s39, s11
	v_readlane_b32 s45, v165, 51
	v_readlane_b32 s46, v165, 52
	v_readlane_b32 s47, v165, 53
	s_add_u32 s44, s44, s10
	v_lshlrev_b64 v[6:7], 4, v[0:1]
	v_add_u32_e32 v56, 0x1000000, v6
	v_add_u32_e32 v57, 0x2000000, v6
	v_add_u32_e32 v58, 0x3000000, v6
	v_add_u32_e32 v59, 0x4000000, v6
	v_add_u32_e32 v60, 0x5000000, v6
	v_add_u32_e32 v61, 0x6000000, v6
	v_add_u32_e32 v62, 0x7000000, v6
	s_addc_u32 s45, s45, s11
	s_mov_b64 s[46:47], 0
	v_readlane_b32 s52, v165, 38
	v_readlane_b32 s53, v165, 39
	v_readlane_b32 s54, v165, 40
	v_readlane_b32 s55, v165, 41
	v_readlane_b32 s48, v165, 54
	v_readlane_b32 s49, v165, 55
	v_readlane_b32 s50, v165, 56
	v_readlane_b32 s51, v165, 57
; __device__ __forceinline__ float gelu_tanh(float x) { const float u = 0.7978845608028654f * (x + 0.044715f * x * x * x); return x / (1.0f + __expf(-2.0f * u)); }
; __device__ __forceinline__ int get_bid() { int b = blockIdx.x; asm volatile("" : "+s"(b)); return b; }
; __device__ __forceinline__ void peer_w_phase(const Params& p, int l) {
;     ...
;     for (size_t i = ((size_t)get_bid() * NTHREADS + tid) * 4; i < (size_t)T * 128; i += (size_t)gridDim.x * NTHREADS * 4) {
;         f32x4 hs = __builtin_nontemporal_load((const f32x4*)(p.part + i));
; #pragma unroll
;         for (int xx = 1; xx < 8; ++xx) hs += __builtin_nontemporal_load((const f32x4*)(p.part + (size_t)xx * T * 128 + i));
;         const int4 e = *(const int4*)(p.experts + i);
;         const f32x4 gt = *(const f32x4*)(p.gates + i);
;         const float* su = p.su + l * 16384; const float* sv = p.sv + l * 16384;
;         f32x4 w;
;         w[0] = gt[0] * gelu_tanh(hs[0] * su[e.x]) * sv[e.x]; w[1] = gt[1] * gelu_tanh(hs[1] * su[e.y]) * sv[e.y];
;         w[2] = gt[2] * gelu_tanh(hs[2] * su[e.z]) * sv[e.z]; w[3] = gt[3] * gelu_tanh(hs[3] * su[e.w]) * sv[e.w];
;         *(f32x4*)(p.wbuf + i) = w;
;     }
.LBB0_28:
	global_load_dwordx4 v[0:3], v6, s[36:37] nt
	global_load_dwordx4 v[68:71], v56, s[36:37] nt
	global_load_dwordx4 v[24:27], v57, s[36:37] nt
	global_load_dwordx4 v[28:31], v58, s[36:37] nt
	global_load_dwordx4 v[32:35], v59, s[36:37] nt
	global_load_dwordx4 v[36:39], v60, s[36:37] nt
	global_load_dwordx4 v[40:43], v61, s[36:37] nt
	global_load_dwordx4 v[44:47], v62, s[36:37] nt
	global_load_dwordx4 v[8:11], v6, s[42:43]
	global_load_dwordx4 v[12:15], v6, s[40:41] offset:-8
	s_add_u32 s36, s36, s14
	s_addc_u32 s37, s37, s15
	s_add_u32 s40, s40, s14
	s_addc_u32 s41, s41, s15
	s_add_u32 s42, s42, s14
	s_addc_u32 s43, s43, s15
	v_lshl_add_u64 v[4:5], v[4:5], 0, s[8:9]
	s_waitcnt vmcnt(8)
	v_pk_add_f32 v[64:65], v[0:1], v[68:69]
	v_pk_add_f32 v[66:67], v[2:3], v[70:71]
	s_waitcnt vmcnt(7)
	v_pk_add_f32 v[64:65], v[64:65], v[24:25]
	v_pk_add_f32 v[66:67], v[66:67], v[26:27]
	s_waitcnt vmcnt(6)
	v_pk_add_f32 v[64:65], v[64:65], v[28:29]
	v_pk_add_f32 v[66:67], v[66:67], v[30:31]
	s_waitcnt vmcnt(5)
	v_pk_add_f32 v[64:65], v[64:65], v[32:33]
	v_pk_add_f32 v[66:67], v[66:67], v[34:35]
	s_waitcnt vmcnt(4)
	v_pk_add_f32 v[64:65], v[64:65], v[36:37]
	v_pk_add_f32 v[66:67], v[66:67], v[38:39]
	s_waitcnt vmcnt(3)
	v_pk_add_f32 v[64:65], v[64:65], v[40:41]
	v_pk_add_f32 v[66:67], v[66:67], v[42:43]
	s_waitcnt vmcnt(2)
	v_pk_add_f32 v[2:3], v[64:65], v[44:45]
	v_pk_add_f32 v[0:1], v[66:67], v[46:47]
	s_waitcnt vmcnt(0)
	v_ashrrev_i32_e32 v17, 31, v12
	v_mov_b32_e32 v16, v12
	v_lshlrev_b64 v[16:17], 2, v[16:17]
	v_lshl_add_u64 v[18:19], s[22:23], 0, v[16:17]
	global_load_dword v12, v[18:19], off
	v_ashrrev_i32_e32 v19, 31, v13
	v_mov_b32_e32 v18, v13
	v_lshlrev_b64 v[18:19], 2, v[18:19]
	v_lshl_add_u64 v[20:21], s[22:23], 0, v[18:19]
	global_load_dword v13, v[20:21], off
	v_lshl_add_u64 v[16:17], s[34:35], 0, v[16:17]
	v_lshl_add_u64 v[18:19], s[34:35], 0, v[18:19]
	global_load_dword v16, v[16:17], off
	s_waitcnt vmcnt(1)
	v_pk_mul_f32 v[2:3], v[2:3], v[12:13]
	global_load_dword v17, v[18:19], off
	v_ashrrev_i32_e32 v19, 31, v14
	v_mov_b32_e32 v18, v14
	v_lshlrev_b64 v[18:19], 2, v[18:19]
	v_lshl_add_u64 v[20:21], s[22:23], 0, v[18:19]
	global_load_dword v14, v[20:21], off
	v_ashrrev_i32_e32 v21, 31, v15
	v_mov_b32_e32 v20, v15
	v_lshlrev_b64 v[20:21], 2, v[20:21]
	v_lshl_add_u64 v[22:23], s[22:23], 0, v[20:21]
	global_load_dword v15, v[22:23], off
	v_lshl_add_u64 v[18:19], s[34:35], 0, v[18:19]
	v_lshl_add_u64 v[20:21], s[34:35], 0, v[20:21]
	global_load_dword v18, v[18:19], off
	v_mul_f32_e32 v12, 0x3d372713, v2
	global_load_dword v19, v[20:21], off
	v_mul_f32_e32 v13, 0x3d372713, v3
	v_mul_f32_e32 v12, v2, v12
	v_mul_f32_e32 v13, v3, v13
	v_fma_f32 v12, v2, v12, v2
	v_fma_f32 v13, v3, v13, v3
	v_mul_f32_e32 v12, 0x3f4c422a, v12
	v_mul_f32_e32 v13, 0x3f4c422a, v13
	v_mul_f32_e32 v12, -2.0, v12
	v_mul_f32_e32 v13, -2.0, v13
	v_mul_f32_e32 v12, 0x3fb8aa3b, v12
	v_mul_f32_e32 v13, 0x3fb8aa3b, v13
	v_exp_f32_e32 v12, v12
	v_exp_f32_e32 v13, v13
	s_waitcnt vmcnt(2)
	v_pk_mul_f32 v[0:1], v[0:1], v[14:15]
	v_pk_add_f32 v[12:13], v[12:13], 1.0 op_sel_hi:[1,0]
	v_mul_f32_e32 v14, 0x3d372713, v0
	v_div_scale_f32 v20, s[10:11], v13, v13, v3
	v_rcp_f32_e32 v21, v20
	v_mul_f32_e32 v15, 0x3d372713, v1
	v_mul_f32_e32 v14, v0, v14
	v_mul_f32_e32 v15, v1, v15
	v_fma_f32 v22, -v20, v21, 1.0
	v_fmac_f32_e32 v21, v22, v21
	v_div_scale_f32 v22, vcc, v3, v13, v3
	v_mul_f32_e32 v23, v22, v21
	v_fma_f32 v24, -v20, v23, v22
	v_fmac_f32_e32 v23, v24, v21
	v_fma_f32 v20, -v20, v23, v22
	v_div_fmas_f32 v20, v20, v21, v23
	v_div_fixup_f32 v3, v20, v13, v3
	v_div_scale_f32 v13, s[10:11], v12, v12, v2
	v_rcp_f32_e32 v20, v13
	v_fma_f32 v14, v0, v14, v0
	v_fma_f32 v15, v1, v15, v1
	v_mul_f32_e32 v14, 0x3f4c422a, v14
	v_mul_f32_e32 v15, 0x3f4c422a, v15
	v_mul_f32_e32 v14, -2.0, v14
	v_mul_f32_e32 v15, -2.0, v15
	v_fma_f32 v21, -v13, v20, 1.0
	v_mul_f32_e32 v14, 0x3fb8aa3b, v14
	v_mul_f32_e32 v15, 0x3fb8aa3b, v15
	v_fmac_f32_e32 v20, v21, v20
	v_div_scale_f32 v21, vcc, v2, v12, v2
	v_exp_f32_e32 v14, v14
	v_exp_f32_e32 v15, v15
	v_mul_f32_e32 v22, v21, v20
	v_fma_f32 v23, -v13, v22, v21
	v_fmac_f32_e32 v22, v23, v20
	v_fma_f32 v13, -v13, v22, v21
	v_pk_add_f32 v[14:15], v[14:15], 1.0 op_sel_hi:[1,0]
	v_div_fmas_f32 v13, v13, v20, v22
	v_div_fixup_f32 v2, v13, v12, v2
	v_div_scale_f32 v12, s[10:11], v15, v15, v1
	v_rcp_f32_e32 v13, v12
	s_nop 0
	v_fma_f32 v20, -v12, v13, 1.0
	v_fmac_f32_e32 v13, v20, v13
	v_div_scale_f32 v20, vcc, v1, v15, v1
	v_mul_f32_e32 v21, v20, v13
	v_fma_f32 v22, -v12, v21, v20
	v_fmac_f32_e32 v21, v22, v13
	v_fma_f32 v12, -v12, v21, v20
	v_div_fmas_f32 v12, v12, v13, v21
	v_div_fixup_f32 v1, v12, v15, v1
	v_div_scale_f32 v12, s[10:11], v14, v14, v0
	v_rcp_f32_e32 v13, v12
	s_mov_b64 s[10:11], 0x3fffff
	v_fma_f32 v15, -v12, v13, 1.0
	v_fmac_f32_e32 v13, v15, v13
	v_div_scale_f32 v15, vcc, v0, v14, v0
	v_mul_f32_e32 v20, v15, v13
	v_fma_f32 v21, -v12, v20, v15
	v_fmac_f32_e32 v20, v21, v13
	v_fma_f32 v12, -v12, v20, v15
	v_div_fmas_f32 v12, v12, v13, v20
	v_div_fixup_f32 v0, v12, v14, v0
	v_pk_mul_f32 v[10:11], v[10:11], v[0:1]
	v_pk_mul_f32 v[0:1], v[8:9], v[2:3]
	v_lshl_add_u64 v[8:9], s[44:45], 0, v[6:7]
	s_add_u32 s44, s44, s14
	s_addc_u32 s45, s45, s15
	v_cmp_lt_u64_e32 vcc, s[10:11], v[4:5]
	v_pk_mul_f32 v[0:1], v[16:17], v[0:1]
	s_waitcnt vmcnt(0)
	v_pk_mul_f32 v[2:3], v[18:19], v[10:11]
	s_or_b64 s[46:47], vcc, s[46:47]
	global_store_dwordx4 v[8:9], v[0:3], off
	s_andn2_b64 exec, exec, s[46:47]
	s_cbranch_execnz .LBB0_28
